# v32 + attention K/V/Q tile loads issued as global (not flat) so LDS waits do not wait on the in-flight prefetch
# speedup vs baseline: 1.0110x; 1.0064x over previous
; #define VMW() asm volatile("s_waitcnt vmcnt(0)" ::: "memory")
; #define SLOAD_H(Kp, k0) do { const bf16_t* kb__ = (Kp) + (size_t)(k0) * PW;     \
;                          S.st_v0 = load8(kb__ + voff0 + VOFF); S.st_v1 = load8(kb__ + voff1 + VOFF);              \
;                          S.st_k0 = load8(kb__ + voff0); S.st_k1 = load8(kb__ + voff1); } while (0)
; #define SWRITE_HK(bf) do { *(bf16x8*)(K_lds + (bf) * SHM_K + kws) = S.st_k0; *(bf16x8*)(K_lds + (bf) * SHM_K + kws + 32 * 256) = S.st_k1; } while (0)
; __device__ __forceinline__ void fox_prime(const BlockRef& cur, char* lds, Seam& S) {
;     int tidl_ = threadIdx.x; asm volatile("" : "+v"(tidl_));
;     const int tid = tidl_, wid = __builtin_amdgcn_readfirstlane(tid >> 6), lane = tid & 63, r32 = lane & 31, hi = lane >> 5;
;     const int sr = tid >> 4, sc = (tid & 15) * 8, kws = KSWZ(sr, sc * 2); char* K_lds = lds + 2 * SHM_V;
;     const unsigned voff0 = (unsigned)(sr * PW + sc), voff1 = voff0 + 32u * PW, voffq = (unsigned)(r32 * PW + hi * 8);
;     { const bf16_t* qb__ = cur.Q + (size_t)(wid * QBLK) * PW;
; #pragma unroll
;     for (int d0 = 0; d0 < 8; ++d0) S.qr[d0] = load8(qb__ + voffq + d0 * 16); }
;     SLOAD_H(cur.K, cur.jlo * KVBLK); VMW(); SWRITE_HK(0);
;     __syncthreads();
; }
.LBB0_763:
	s_mul_i32 s3, s30, 0x3000
	s_add_u32 s3, s38, s3
	s_addc_u32 s8, s39, 0
	s_lshl_b32 s9, s22, 8
	s_add_u32 s3, s3, s9
	s_addc_u32 s8, s8, 0
	s_add_u32 s66, s3, 0x1800
	s_addc_u32 s67, s8, 0
	s_add_u32 s68, s37, s9
	s_addc_u32 s69, s34, 0
	s_lshl_b32 s3, s30, 12
	s_add_u32 s3, s43, s3
	s_addc_u32 s8, s40, 0
	s_add_u32 s3, s3, s9
	s_addc_u32 s8, s8, 0
	s_add_u32 s70, s3, 0x800
	v_readfirstlane_b32 s3, v3
	v_mov_b32_e32 v3, v194
	s_addc_u32 s71, s8, 0
	s_nop 0
	v_readfirstlane_b32 s8, v3
	s_ashr_i32 s8, s8, 1
	v_and_b32_e32 v4, 31, v3
	s_andn2_b32 s8, s8, 31
	v_mul_u32_u24_e32 v4, 0x1800, v4
	v_lshrrev_b32_e32 v5, 2, v3
	s_mul_hi_i32 s9, s8, 0x3000
	s_mulk_i32 s8, 0x3000
	v_and_or_b32 v4, v5, 8, v4
	s_add_u32 s8, s66, s8
	s_addc_u32 s9, s67, s9
	v_lshlrev_b32_e32 v196, 1, v4
	v_lshl_add_u64 v[4:5], s[8:9], 0, v[196:197]
	global_load_dwordx4 v[154:157], v[4:5], off
	global_load_dwordx4 v[130:133], v[4:5], off offset:32
	v_ashrrev_i32_e32 v10, 4, v3
	v_lshlrev_b32_e32 v7, 3, v3
	s_lshl_b32 s8, s3, 6
	s_mul_i32 s9, s3, 0xc0000
	v_mul_lo_u32 v6, v10, s92
	v_and_b32_e32 v11, 0x78, v7
	s_mul_hi_i32 s10, s8, 0x3000
	s_add_u32 s8, s68, s9
	v_or_b32_e32 v196, v6, v11
	s_addc_u32 s9, s69, s10
	v_add_u32_e32 v6, 0x30000, v196
	v_lshl_add_u64 v[8:9], v[196:197], 1, s[8:9]
	v_mov_b32_e32 v7, v197
	v_lshl_add_u64 v[6:7], v[6:7], 1, s[8:9]
	global_load_dwordx4 v[98:101], v[8:9], off offset:2048
	global_load_dwordx4 v[102:105], v[8:9], off
	global_load_dwordx4 v[106:109], v[6:7], off offset:2048
	global_load_dwordx4 v[110:113], v[6:7], off
	global_load_dwordx4 v[158:161], v[4:5], off offset:64
	global_load_dwordx4 v[138:141], v[4:5], off offset:96
	global_load_dwordx4 v[142:145], v[4:5], off offset:128
	global_load_dwordx4 v[146:149], v[4:5], off offset:160
	global_load_dwordx4 v[150:153], v[4:5], off offset:192
	global_load_dwordx4 v[134:137], v[4:5], off offset:224
	s_movk_i32 s8, 0x70
	v_lshlrev_b32_e32 v5, 1, v11
	s_waitcnt vmcnt(0)
	v_lshlrev_b32_e32 v4, 8, v10
	v_bitop3_b32 v3, v5, v3, s8 bitop3:0x78
	v_add3_u32 v3, s87, v4, v3
	v_cmp_lt_u32_e64 s[8:9], 63, v2
	s_waitcnt vmcnt(0) lgkmcnt(0)
	ds_write_b128 v3, v[102:105] offset:32768
	ds_write_b128 v3, v[110:113] offset:40960
	s_waitcnt lgkmcnt(0)
	s_barrier
	s_branch .LBB0_765

; #define SBAR() __builtin_amdgcn_sched_barrier(0)
; __device__ __forceinline__ int v_st(int k, int c) { const int kk = (k & ~0xC) | ((k & 4) << 1) | ((k & 8) >> 1); return ((kk >> 3) * 4 + (c >> 5)) * 512 + ((kk & 7) * 32 + (c & 31)) * 2; }
; __device__ __forceinline__ int v_rd_base(int lane) { return ((lane & 3) << 3) | (((lane >> 2) & 3) << 6) | (((lane >> 4) & 1) << 5) | (((lane >> 5) & 1) << 8); }
; #define SLOAD_H(Kp, k0) do { const bf16_t* kb__ = (Kp) + (size_t)(k0) * PW;     \
;                          S.st_v0 = load8(kb__ + voff0 + VOFF); S.st_v1 = load8(kb__ + voff1 + VOFF);              \
;                          S.st_k0 = load8(kb__ + voff0); S.st_k1 = load8(kb__ + voff1); } while (0)
; #define SWRITE_HV(bf) do { *(bf16x8*)(V_lds + (bf) * SHM_V + vst0) = S.st_v0; *(bf16x8*)(V_lds + (bf) * SHM_V + vst1) = S.st_v1; } while (0)
; __device__ __forceinline__ bool fox_block(const BlockRef& cur, BlockRef& nxt, unsigned* ctr, const unsigned* nrm, bf16_t* PROJ, bf16_t* MIX, char* lds, Seam& S, const float* __restrict__ CF, const float* __restrict__ fnorm) {
;     ...
;     const int sr = tid >> 4, sc = (tid & 15) * 8, vst0 = v_st(sr, sc), vst1 = v_st(32 + sr, sc), kws = KSWZ(sr, sc * 2);
;     const int vb0 = (int)(uintptr_t)V_lds + v_rd_base(lane);
;     const bf16_t* Kh = cur.K;
;     const unsigned voff0 = (unsigned)(sr * PW + sc), voff1 = voff0 + 32u * PW, voffq = (unsigned)(r32 * PW + hi * 8);
;     ...
;     f32x16 pA0, pA1, pB0, pB1; float mnA, mnB, alA, alB; bf16x8 pa0, pa1, pa2, pa3;
;     SWRITE_HV(0); SBAR();
;     if (NT > 1) SLOAD_H(Kh, KBASE(1));
.LBB0_773:
	s_or_b64 exec, exec, s[10:11]
	v_ashrrev_i32_e32 v36, 4, v202
	v_add_u32_e32 v7, 32, v36
	v_and_b32_e32 v4, 0xfffff0, v36
	v_lshlrev_b32_e32 v5, 1, v36
	v_and_b32_e32 v8, 0xfffff0, v7
	v_lshlrev_b32_e32 v7, 1, v7
	s_waitcnt vmcnt(0) lgkmcnt(0)
	v_lshlrev_b32_e32 v2, 3, v202
	v_and_or_b32 v4, v5, 8, v4
	v_and_or_b32 v7, v7, 8, v8
	v_and_b32_e32 v3, 0x78, v2
	v_lshrrev_b32_e32 v5, 1, v36
	v_lshrrev_b32_e32 v4, 1, v4
	v_bfe_u32 v2, v2, 5, 2
	v_and_b32_e32 v6, 3, v36
	v_lshrrev_b32_e32 v7, 1, v7
	v_or_b32_e32 v4, v4, v2
	v_and_or_b32 v5, v5, 4, v6
	v_lshlrev_b32_e32 v37, 1, v3
	v_or_b32_e32 v2, v7, v2
	v_lshlrev_b32_e32 v4, 9, v4
	v_lshlrev_b32_e32 v5, 6, v5
	v_and_b32_e32 v6, 48, v37
	v_lshlrev_b32_e32 v2, 9, v2
	v_or3_b32 v4, v4, v5, v6
	v_or3_b32 v2, v2, v5, v6
	v_mul_lo_u32 v5, v36, s92
	v_or_b32_e32 v196, v5, v3
	v_add_u32_e32 v204, 0x30000, v196
	v_add_u32_e32 v224, 0x100, v4
	v_add_u32_e32 v225, 0x100, v2
	s_barrier
	ds_write_b128 v224, v[98:101]
	ds_write_b128 v225, v[106:109]
	s_cmp_gt_i32 s76, 1
	s_cselect_b64 s[12:13], -1, 0
	s_and_b64 vcc, exec, s[12:13]
	s_cbranch_vccz .LBB0_775
	s_add_i32 s10, s84, 64
	s_mul_hi_i32 s11, s10, 0x3000
	s_mulk_i32 s10, 0x3000
	s_add_u32 s10, s68, s10
	s_addc_u32 s11, s69, s11
	v_lshl_add_u64 v[2:3], v[196:197], 1, s[10:11]
	v_mov_b32_e32 v205, v197
	v_lshl_add_u64 v[4:5], v[204:205], 1, s[10:11]
	global_load_dwordx4 v[98:101], v[2:3], off offset:2048
	global_load_dwordx4 v[102:105], v[2:3], off
	global_load_dwordx4 v[106:109], v[4:5], off offset:2048
	global_load_dwordx4 v[110:113], v[4:5], off

; __device__ __forceinline__ void finishSM(f32x16& p0, f32x16& p1, float alpha, float& l_reg, bf16x8& pa0, bf16x8& pa1, bf16x8& pa2, bf16x8& pa3) {
; #pragma unroll
;     for (int r = 0; r < 16; ++r) p1[r] = __builtin_amdgcn_exp2f(p1[r]);
;     float ps = 0;
; #pragma unroll
;     for (int r = 0; r < 16; ++r) ps += p0[r];
; #pragma unroll
;     for (int r = 0; r < 16; ++r) ps += p1[r];
;     { auto rr = __builtin_amdgcn_permlane32_swap(__float_as_uint(ps), __float_as_uint(ps), false, false);
;       ps = __uint_as_float(rr[0]) + __uint_as_float(rr[1]); }
;     l_reg = l_reg * alpha + ps;
;     ...
;     PK4(p0, 0, pa0); PK4(p0, 8, pa1); PK4(p1, 0, pa2); PK4(p1, 8, pa3);
;     ...
; }
; template <int KB>
; __device__ __forceinline__ void qkt(f32x16& p0, f32x16& p1, const char* K_lds, int r32, int hi, const bf16x8* qr, const float* btile) {
; #pragma unroll
;     for (int j = 0; j < 4; ++j) { const f32x4 a = *(const f32x4*)(btile + 8 * j), b = *(const f32x4*)(btile + 32 + 8 * j);
;         p0[4 * j] = a[0]; p0[4 * j + 1] = a[1]; p0[4 * j + 2] = a[2]; p0[4 * j + 3] = a[3];
;         p1[4 * j] = b[0]; p1[4 * j + 1] = b[1]; p1[4 * j + 2] = b[2]; p1[4 * j + 3] = b[3]; }
;     const char* kb[4];
; #pragma unroll
;     for (int dd = 0; dd < 4; ++dd) kb[dd] = K_lds + KB * SHM_K + KSWZ(r32, (dd * 16 + hi * 8) * 2);
; #pragma unroll
;     for (int d0 = 0; d0 < 8; ++d0) { const char* a = kb[d0 & 3] + (d0 >> 2) * 128;
;         bf16x8 b0 = *reinterpret_cast<const bf16x8*>(a);
;         bf16x8 b1 = *reinterpret_cast<const bf16x8*>(a + 32 * 256);
;         p0 = __builtin_amdgcn_mfma_f32_32x32x16_bf16(b0, qr[d0], p0, 0, 0, 0);
;         p1 = __builtin_amdgcn_mfma_f32_32x32x16_bf16(b1, qr[d0], p1, 0, 0, 0); }
; }
.LBB0_783:
	ds_read_b128 v[82:85], v201 offset:49152
	ds_read_b128 v[66:69], v226
	ds_read_b128 v[70:73], v226 offset:32
	ds_read_b128 v[74:77], v226 offset:64
	ds_read_b128 v[78:81], v226 offset:96
	s_waitcnt vmcnt(0)
	ds_read_b128 v[98:101], v201 offset:57344
	ds_read_b128 v[102:105], v201 offset:49280
	v_exp_f32_e32 v128, v128
	v_exp_f32_e32 v129, v129
	s_waitcnt lgkmcnt(2)
	v_mfma_f32_32x32x16_bf16 v[66:81], v[82:85], v[154:157], v[66:81]
	ds_read_b128 v[82:85], v226 offset:128
	ds_read_b128 v[86:89], v226 offset:160
	ds_read_b128 v[90:93], v226 offset:192
	ds_read_b128 v[94:97], v226 offset:224
	ds_read_b128 v[106:109], v201 offset:57472
	v_exp_f32_e32 v126, v126
	v_exp_f32_e32 v127, v127
	v_exp_f32_e32 v124, v124
	v_exp_f32_e32 v125, v125
	v_exp_f32_e32 v122, v122
	v_exp_f32_e32 v123, v123
	s_waitcnt lgkmcnt(1)
	v_mfma_f32_32x32x16_bf16 v[82:97], v[98:101], v[154:157], v[82:97]
	ds_read_b128 v[98:101], v221 offset:49152
	ds_read_b128 v[110:113], v221 offset:57344
	ds_read_b128 v[180:183], v221 offset:49280
	v_exp_f32_e32 v120, v120
	v_exp_f32_e32 v121, v121
	v_exp_f32_e32 v118, v118
	v_exp_f32_e32 v119, v119
	v_exp_f32_e32 v116, v116
	v_exp_f32_e32 v117, v117
	s_waitcnt lgkmcnt(2)
	v_mfma_f32_32x32x16_bf16 v[66:81], v[98:101], v[130:133], v[66:81]
	ds_read_b128 v[184:187], v221 offset:57472
	ds_read_b128 v[98:101], v222 offset:49152
	ds_read_b128 v[188:191], v222 offset:49280
	ds_read_b128 v[228:231], v222 offset:57344
	ds_read_b128 v[232:235], v222 offset:57472
	ds_read_b128 v[236:239], v223 offset:49152
	ds_read_b128 v[240:243], v223 offset:49280
	v_exp_f32_e32 v114, v114
	v_exp_f32_e32 v115, v115
	s_waitcnt lgkmcnt(8)
	v_mfma_f32_32x32x16_bf16 v[82:97], v[110:113], v[130:133], v[82:97]
	ds_read_b128 v[110:113], v223 offset:57344
	ds_read_b128 v[244:247], v223 offset:57472
	s_waitcnt lgkmcnt(7)
	v_mfma_f32_32x32x16_bf16 v[66:81], v[98:101], v[158:161], v[66:81]
	v_add_f32_e32 v98, 0, v175
	v_add_f32_e32 v98, v177, v98
	v_add_f32_e32 v98, v173, v98
	v_add_f32_e32 v98, v176, v98
	v_add_f32_e32 v98, v172, v98
	v_add_f32_e32 v98, v174, v98
	v_add_f32_e32 v98, v170, v98
	s_waitcnt lgkmcnt(5)
	v_mfma_f32_32x32x16_bf16 v[82:97], v[228:231], v[158:161], v[82:97]
	v_add_f32_e32 v98, v171, v98
	v_add_f32_e32 v98, v166, v98
	v_add_f32_e32 v98, v169, v98
	v_add_f32_e32 v98, v164, v98
	v_add_f32_e32 v98, v167, v98
	v_add_f32_e32 v98, v162, v98
	v_add_f32_e32 v98, v168, v98
	s_waitcnt lgkmcnt(3)
	v_mfma_f32_32x32x16_bf16 v[66:81], v[236:239], v[138:141], v[66:81]
	v_add_f32_e32 v98, v163, v98
	v_add_f32_e32 v98, v165, v98
	v_add_f32_e32 v98, v128, v98
	v_add_f32_e32 v98, v129, v98
	v_add_f32_e32 v98, v126, v98
	v_add_f32_e32 v98, v127, v98
	v_add_f32_e32 v98, v124, v98
	s_waitcnt lgkmcnt(1)
	v_mfma_f32_32x32x16_bf16 v[82:97], v[110:113], v[138:141], v[82:97]
	v_add_f32_e32 v98, v125, v98
	v_add_f32_e32 v98, v122, v98
	v_add_f32_e32 v98, v123, v98
	v_add_f32_e32 v98, v120, v98
	v_add_f32_e32 v98, v121, v98
	v_add_f32_e32 v98, v118, v98
	v_add_f32_e32 v98, v119, v98
	v_mfma_f32_32x32x16_bf16 v[66:81], v[102:105], v[142:145], v[66:81]
	v_add_f32_e32 v98, v116, v98
	v_add_f32_e32 v98, v117, v98
	v_add_f32_e32 v98, v114, v98
	v_add_f32_e32 v228, v115, v98
	v_mov_b32_e32 v229, v228
	s_nop 1
	v_permlane32_swap_b32_e32 v228, v229
	v_mfma_f32_32x32x16_bf16 v[82:97], v[106:109], v[142:145], v[82:97]
	v_cvt_pk_bf16_f32 v98, v175, v177
	v_cvt_pk_bf16_f32 v99, v173, v176
	v_cvt_pk_bf16_f32 v100, v172, v174
	v_cvt_pk_bf16_f32 v101, v170, v171
	v_cvt_pk_bf16_f32 v102, v166, v169
	v_cvt_pk_bf16_f32 v103, v164, v167
	v_cvt_pk_bf16_f32 v104, v162, v168
	v_mfma_f32_32x32x16_bf16 v[66:81], v[180:183], v[146:149], v[66:81]
	v_cvt_pk_bf16_f32 v105, v163, v165
	v_cvt_pk_bf16_f32 v106, v128, v129
	v_cvt_pk_bf16_f32 v107, v126, v127
	v_cvt_pk_bf16_f32 v108, v124, v125
	v_cvt_pk_bf16_f32 v109, v122, v123
	v_cvt_pk_bf16_f32 v110, v120, v121
	v_cvt_pk_bf16_f32 v111, v118, v119
	v_mfma_f32_32x32x16_bf16 v[82:97], v[184:187], v[146:149], v[82:97]
	v_cvt_pk_bf16_f32 v112, v116, v117
	v_cvt_pk_bf16_f32 v113, v114, v115
	v_permlane32_swap_b32_e32 v98, v100
	v_permlane32_swap_b32_e32 v99, v101
	v_permlane32_swap_b32_e32 v102, v104
	v_mfma_f32_32x32x16_bf16 v[66:81], v[188:191], v[150:153], v[66:81]
	v_permlane32_swap_b32_e32 v103, v105
	v_permlane32_swap_b32_e32 v106, v108
	v_permlane32_swap_b32_e32 v107, v109
	v_permlane32_swap_b32_e32 v110, v112
	v_mfma_f32_32x32x16_bf16 v[82:97], v[232:235], v[150:153], v[82:97]
	v_permlane32_swap_b32_e32 v111, v113
	v_mfma_f32_32x32x16_bf16 v[66:81], v[240:243], v[134:137], v[66:81]
	s_waitcnt lgkmcnt(0)
	v_mfma_f32_32x32x16_bf16 v[82:97], v[244:247], v[134:137], v[82:97]
	s_add_i32 s12, s78, 1
	s_mul_hi_i32 s13, s12, 0x3000
	s_mulk_i32 s12, 0x3000
	s_add_u32 s12, s68, s12
	s_addc_u32 s13, s69, s13
	v_lshl_add_u64 v[114:115], v[196:197], 1, s[12:13]
	v_lshl_add_u64 v[116:117], v[204:205], 1, s[12:13]
	global_load_dwordx4 v[162:165], v[114:115], off offset:2048
	global_load_dwordx4 v[166:169], v[114:115], off
	global_load_dwordx4 v[170:173], v[116:117], off offset:2048
	global_load_dwordx4 v[174:177], v[116:117], off
	ds_read_b64_tr_b16 v[114:115], v216 offset:0
	ds_read_b64_tr_b16 v[116:117], v216 offset:0x800
	ds_read_b64_tr_b16 v[118:119], v216 offset:0x1000
	ds_read_b64_tr_b16 v[120:121], v216 offset:0x1800
	ds_read_b64_tr_b16 v[122:123], v216 offset:0x2000
	ds_read_b64_tr_b16 v[124:125], v216 offset:0x2800
	ds_read_b64_tr_b16 v[126:127], v216 offset:0x3000
	ds_read_b64_tr_b16 v[128:129], v216 offset:0x3800
	s_waitcnt lgkmcnt(0)
; __device__ __forceinline__ void mask_tile(f32x16& p0, f32x16& p1, int dq, unsigned W) {
;     const float NEG = -__builtin_inff();
; #pragma unroll
;     for (int r = 0; r < 16; ++r) {
;         const int c = (r & 3) + 8 * (r >> 2);
;         if ((unsigned)(dq - c) >= W) p0[r] = NEG;
;         if ((unsigned)(dq - c - 32) >= W) p1[r] = NEG;
;     }
; }
; template <int VB>
; __device__ __forceinline__ void pv_tile(f32x16* o, int vb0, bf16x8 pa0, bf16x8 pa1, bf16x8 pa2, bf16x8 pa3) {
;     ...
;     PV_D0(0); PV_D0(1); PV_D0(2); PV_D0(3);
;     ...
; }
	s_nop 0
	v_mfma_f32_32x32x16_bf16 v[50:65], v[98:101], v[114:117], v[50:65]
	ds_read_b64_tr_b16 v[114:115], v216 offset:0x200
	ds_read_b64_tr_b16 v[116:117], v216 offset:0xa00
	v_mfma_f32_32x32x16_bf16 v[50:65], v[102:105], v[118:121], v[50:65]
	ds_read_b64_tr_b16 v[118:119], v216 offset:0x1200
	ds_read_b64_tr_b16 v[120:121], v216 offset:0x1a00
	v_mfma_f32_32x32x16_bf16 v[50:65], v[106:109], v[122:125], v[50:65]
	ds_read_b64_tr_b16 v[122:123], v216 offset:0x2200
	ds_read_b64_tr_b16 v[124:125], v216 offset:0x2a00
	ds_read_b64_tr_b16 v[180:181], v216 offset:0x3200
	ds_read_b64_tr_b16 v[182:183], v216 offset:0x3a00
	s_waitcnt lgkmcnt(0)
	v_mfma_f32_32x32x16_bf16 v[50:65], v[110:113], v[126:129], v[50:65]
	v_mfma_f32_32x32x16_bf16 v[34:49], v[98:101], v[114:117], v[34:49]
	ds_read_b64_tr_b16 v[114:115], v216 offset:0x400
	ds_read_b64_tr_b16 v[116:117], v216 offset:0xc00
	v_mfma_f32_32x32x16_bf16 v[34:49], v[102:105], v[118:121], v[34:49]
	ds_read_b64_tr_b16 v[118:119], v216 offset:0x1400
	ds_read_b64_tr_b16 v[120:121], v216 offset:0x1c00
	v_mfma_f32_32x32x16_bf16 v[34:49], v[106:109], v[122:125], v[34:49]
	ds_read_b64_tr_b16 v[122:123], v216 offset:0x2400
	ds_read_b64_tr_b16 v[124:125], v216 offset:0x2c00
	ds_read_b64_tr_b16 v[126:127], v216 offset:0x3400
	ds_read_b64_tr_b16 v[128:129], v216 offset:0x3c00
	s_waitcnt lgkmcnt(0)
	v_mfma_f32_32x32x16_bf16 v[34:49], v[110:113], v[180:183], v[34:49]
	v_mfma_f32_32x32x16_bf16 v[18:33], v[98:101], v[114:117], v[18:33]
	ds_read_b64_tr_b16 v[114:115], v216 offset:0x600
	ds_read_b64_tr_b16 v[116:117], v216 offset:0xe00
	v_mfma_f32_32x32x16_bf16 v[18:33], v[102:105], v[118:121], v[18:33]
	ds_read_b64_tr_b16 v[118:119], v216 offset:0x1600
	ds_read_b64_tr_b16 v[120:121], v216 offset:0x1e00
	v_mfma_f32_32x32x16_bf16 v[18:33], v[106:109], v[122:125], v[18:33]
	ds_read_b64_tr_b16 v[122:123], v216 offset:0x2600
	ds_read_b64_tr_b16 v[124:125], v216 offset:0x2e00
	ds_read_b64_tr_b16 v[180:181], v216 offset:0x3600
	ds_read_b64_tr_b16 v[182:183], v216 offset:0x3e00
	s_waitcnt lgkmcnt(0)
	v_mfma_f32_32x32x16_bf16 v[18:33], v[110:113], v[126:129], v[18:33]
	v_mfma_f32_32x32x16_bf16 v[2:17], v[98:101], v[114:117], v[2:17]
	s_cmp_le_i32 s78, s73
	v_mfma_f32_32x32x16_bf16 v[2:17], v[102:105], v[118:121], v[2:17]
	v_mfma_f32_32x32x16_bf16 v[2:17], v[106:109], v[122:125], v[2:17]
	v_mfma_f32_32x32x16_bf16 v[2:17], v[110:113], v[180:183], v[2:17]
	s_cbranch_scc1 .LBB0_785
	v_add_u32_e32 v98, 0x4000007b, v227
	v_cmp_gt_u32_e32 vcc, 2.0, v98
	v_add_u32_e32 v98, 0x5b, v227
	s_nop 0
	v_cndmask_b32_e32 v66, v208, v66, vcc
	v_cmp_lt_u32_e32 vcc, s95, v98
	v_add_u32_e32 v98, 0x7a, v227
	s_nop 0
	v_cndmask_b32_e32 v82, v208, v82, vcc
	v_cmp_lt_u32_e32 vcc, s95, v98
	v_add_u32_e32 v98, 0x5a, v227
	s_nop 0
	v_cndmask_b32_e32 v67, v208, v67, vcc
	v_cmp_lt_u32_e32 vcc, s95, v98
	v_add_u32_e32 v98, 0x79, v227
	s_nop 0
	v_cndmask_b32_e32 v83, v208, v83, vcc
	v_cmp_lt_u32_e32 vcc, s95, v98
	v_add_u32_e32 v98, 0x59, v227
	s_nop 0
	v_cndmask_b32_e32 v68, v208, v68, vcc
	v_cmp_lt_u32_e32 vcc, s95, v98
	v_add_u32_e32 v98, 0x78, v227
	s_nop 0
	v_cndmask_b32_e32 v84, v208, v84, vcc
	v_cmp_lt_u32_e32 vcc, s95, v98
	v_add_u32_e32 v98, 0x58, v227
	s_nop 0
	v_cndmask_b32_e32 v69, v208, v69, vcc
	v_cmp_lt_u32_e32 vcc, s95, v98
	v_add_u32_e32 v98, 0x73, v227
	s_nop 0
	v_cndmask_b32_e32 v85, v208, v85, vcc
	v_cmp_lt_u32_e32 vcc, s95, v98
	v_add_u32_e32 v98, 0x53, v227
	s_nop 0
	v_cndmask_b32_e32 v70, v208, v70, vcc
	v_cmp_lt_u32_e32 vcc, s95, v98
	v_add_u32_e32 v98, 0x72, v227
	s_nop 0
	v_cndmask_b32_e32 v86, v208, v86, vcc
	v_cmp_lt_u32_e32 vcc, s95, v98
	v_add_u32_e32 v98, 0x52, v227
	s_nop 0
	v_cndmask_b32_e32 v71, v208, v71, vcc
	v_cmp_lt_u32_e32 vcc, s95, v98
	v_add_u32_e32 v98, 0x71, v227
	s_nop 0
	v_cndmask_b32_e32 v87, v208, v87, vcc
	v_cmp_lt_u32_e32 vcc, s95, v98
	v_add_u32_e32 v98, 0x51, v227
	s_nop 0
	v_cndmask_b32_e32 v72, v208, v72, vcc
	v_cmp_lt_u32_e32 vcc, s95, v98
	v_add_u32_e32 v98, 0x70, v227
	s_nop 0
	v_cndmask_b32_e32 v88, v208, v88, vcc
	v_cmp_lt_u32_e32 vcc, s95, v98
	v_add_u32_e32 v98, 0x50, v227
	s_nop 0
	v_cndmask_b32_e32 v73, v208, v73, vcc
	v_cmp_lt_u32_e32 vcc, s95, v98
	v_add_u32_e32 v98, 0x6b, v227
	s_nop 0
	v_cndmask_b32_e32 v89, v208, v89, vcc
	v_cmp_lt_u32_e32 vcc, s95, v98
	v_add_u32_e32 v98, 0x4b, v227
	s_nop 0
	v_cndmask_b32_e32 v74, v208, v74, vcc
	v_cmp_lt_u32_e32 vcc, s95, v98
	v_add_u32_e32 v98, 0x6a, v227
	s_nop 0
	v_cndmask_b32_e32 v90, v208, v90, vcc
	v_cmp_lt_u32_e32 vcc, s95, v98
	v_add_u32_e32 v98, 0x4a, v227
	s_nop 0
	v_cndmask_b32_e32 v75, v208, v75, vcc
	v_cmp_lt_u32_e32 vcc, s95, v98
	v_add_u32_e32 v98, 0x69, v227
	s_nop 0
	v_cndmask_b32_e32 v91, v208, v91, vcc
	v_cmp_lt_u32_e32 vcc, s95, v98
	v_add_u32_e32 v98, 0x49, v227
	s_nop 0
	v_cndmask_b32_e32 v76, v208, v76, vcc
	v_cmp_lt_u32_e32 vcc, s95, v98
	v_add_u32_e32 v98, 0x68, v227
	s_nop 0
	v_cndmask_b32_e32 v92, v208, v92, vcc
	v_cmp_lt_u32_e32 vcc, s95, v98
	v_add_u32_e32 v98, 0x48, v227
	s_nop 0
	v_cndmask_b32_e32 v77, v208, v77, vcc
	v_cmp_lt_u32_e32 vcc, s95, v98
	v_add_u32_e32 v98, 0x63, v227
	s_nop 0
	v_cndmask_b32_e32 v93, v208, v93, vcc
	v_cmp_lt_u32_e32 vcc, s95, v98
	v_add_u32_e32 v98, 0x43, v227
	s_nop 0
	v_cndmask_b32_e32 v78, v208, v78, vcc
	v_cmp_lt_u32_e32 vcc, s95, v98
	v_add_u32_e32 v98, 0x62, v227
	s_nop 0
	v_cndmask_b32_e32 v94, v208, v94, vcc
	v_cmp_lt_u32_e32 vcc, s95, v98
	v_add_u32_e32 v98, 0x42, v227
	s_nop 0
	v_cndmask_b32_e32 v79, v208, v79, vcc
	v_cmp_lt_u32_e32 vcc, s95, v98
	v_add_u32_e32 v98, 0x61, v227
	s_nop 0
	v_cndmask_b32_e32 v95, v208, v95, vcc
	v_cmp_lt_u32_e32 vcc, s95, v98
	v_add_u32_e32 v98, 0x41, v227
	s_nop 0
	v_cndmask_b32_e32 v80, v208, v80, vcc
	v_cmp_lt_u32_e32 vcc, s95, v98
	v_add_u32_e32 v98, 0x60, v227
	s_nop 0
	v_cndmask_b32_e32 v96, v208, v96, vcc
	v_cmp_lt_u32_e32 vcc, s95, v98
	v_add_u32_e32 v98, 64, v227
	s_nop 0
	v_cndmask_b32_e32 v81, v208, v81, vcc
	v_cmp_lt_u32_e32 vcc, s95, v98
	s_nop 1
	v_cndmask_b32_e32 v97, v208, v97, vcc

; __device__ __forceinline__ void partialSM(f32x16& p0, f32x16& p1, float& m_reg, float& mn, float& alpha) {
;     ...
;     constexpr float C2 = 1.4426950408889634f * SCALE;
;     if (__builtin_expect(__all((pmax - m_reg) * SCALE <= THR), 1)) { mn = m_reg; alpha = 1.f; }
;     else { mn = fmaxf(m_reg, pmax); alpha = __builtin_amdgcn_exp2f((m_reg - mn) * C2); m_reg = mn; }
;     const float mnL = -mn * C2;
; #pragma unroll
;     for (int r = 0; r < 16; ++r) p0[r] = fmaf(p0[r], C2, mnL);
; #pragma unroll
;     for (int r = 0; r < 16; ++r) p1[r] = fmaf(p1[r], C2, mnL);
; #pragma unroll
;     for (int r = 0; r < 16; ++r) p0[r] = __builtin_amdgcn_exp2f(p0[r]);
; }
.LBB0_789:
	v_cndmask_b32_e64 v231, v98, v178, s[12:13]
	v_mul_f32_e32 v178, 0xbe0293ee, v231
	v_fmamk_f32 v66, v66, 0x3e0293ee, v178
	v_fmamk_f32 v67, v67, 0x3e0293ee, v178
	v_fmamk_f32 v68, v68, 0x3e0293ee, v178
	v_fmamk_f32 v69, v69, 0x3e0293ee, v178
	v_fmamk_f32 v70, v70, 0x3e0293ee, v178
	v_fmamk_f32 v71, v71, 0x3e0293ee, v178
	v_fmamk_f32 v72, v72, 0x3e0293ee, v178
	v_fmamk_f32 v73, v73, 0x3e0293ee, v178
	v_fmamk_f32 v74, v74, 0x3e0293ee, v178
	v_fmamk_f32 v75, v75, 0x3e0293ee, v178
	v_fmamk_f32 v76, v76, 0x3e0293ee, v178
	v_fmamk_f32 v77, v77, 0x3e0293ee, v178
	v_fmamk_f32 v78, v78, 0x3e0293ee, v178
	v_fmamk_f32 v79, v79, 0x3e0293ee, v178
	v_fmamk_f32 v80, v80, 0x3e0293ee, v178
	v_fmamk_f32 v81, v81, 0x3e0293ee, v178
	v_exp_f32_e32 v66, v66
	v_exp_f32_e32 v67, v67
	v_exp_f32_e32 v68, v68
	v_exp_f32_e32 v69, v69
	v_exp_f32_e32 v70, v70
	v_exp_f32_e32 v71, v71
	v_exp_f32_e32 v72, v72
	v_exp_f32_e32 v73, v73
	v_exp_f32_e32 v74, v74
	v_exp_f32_e32 v75, v75
	v_exp_f32_e32 v76, v76
	v_exp_f32_e32 v77, v77
	v_exp_f32_e32 v78, v78
	v_exp_f32_e32 v79, v79
	v_exp_f32_e32 v80, v80
	v_exp_f32_e32 v81, v81
	v_fmamk_f32 v82, v82, 0x3e0293ee, v178
	v_fmamk_f32 v83, v83, 0x3e0293ee, v178
	v_fmamk_f32 v84, v84, 0x3e0293ee, v178
	v_fmamk_f32 v85, v85, 0x3e0293ee, v178
	v_fmamk_f32 v86, v86, 0x3e0293ee, v178
	v_fmamk_f32 v87, v87, 0x3e0293ee, v178
	v_fmamk_f32 v88, v88, 0x3e0293ee, v178
	v_fmamk_f32 v89, v89, 0x3e0293ee, v178
	v_fmamk_f32 v90, v90, 0x3e0293ee, v178
	v_fmamk_f32 v91, v91, 0x3e0293ee, v178
	v_fmamk_f32 v92, v92, 0x3e0293ee, v178
	v_fmamk_f32 v93, v93, 0x3e0293ee, v178
	v_fmamk_f32 v94, v94, 0x3e0293ee, v178
	v_fmamk_f32 v95, v95, 0x3e0293ee, v178
	v_fmamk_f32 v96, v96, 0x3e0293ee, v178
	v_fmac_f32_e32 v178, 0x3e0293ee, v97
	s_waitcnt lgkmcnt(0)
	s_barrier
; __device__ __forceinline__ void finishSM(f32x16& p0, f32x16& p1, float alpha, float& l_reg, bf16x8& pa0, bf16x8& pa1, bf16x8& pa2, bf16x8& pa3) {
; #pragma unroll
;     for (int r = 0; r < 16; ++r) p1[r] = __builtin_amdgcn_exp2f(p1[r]);
;     float ps = 0;
; #pragma unroll
;     for (int r = 0; r < 16; ++r) ps += p0[r];
; #pragma unroll
;     for (int r = 0; r < 16; ++r) ps += p1[r];
;     { auto rr = __builtin_amdgcn_permlane32_swap(__float_as_uint(ps), __float_as_uint(ps), false, false);
;       ps = __uint_as_float(rr[0]) + __uint_as_float(rr[1]); }
;     l_reg = l_reg * alpha + ps;
; template <int KB>
; __device__ __forceinline__ void qkt(f32x16& p0, f32x16& p1, const char* K_lds, int r32, int hi, const bf16x8* qr, const float* btile) {
; #pragma unroll
;     for (int j = 0; j < 4; ++j) { const f32x4 a = *(const f32x4*)(btile + 8 * j), b = *(const f32x4*)(btile + 32 + 8 * j);
;         p0[4 * j] = a[0]; p0[4 * j + 1] = a[1]; p0[4 * j + 2] = a[2]; p0[4 * j + 3] = a[3];
;         p1[4 * j] = b[0]; p1[4 * j + 1] = b[1]; p1[4 * j + 2] = b[2]; p1[4 * j + 3] = b[3]; }
;     const char* kb[4];
; #pragma unroll
;     for (int dd = 0; dd < 4; ++dd) kb[dd] = K_lds + KB * SHM_K + KSWZ(r32, (dd * 16 + hi * 8) * 2);
; #pragma unroll
;     for (int d0 = 0; d0 < 8; ++d0) { const char* a = kb[d0 & 3] + (d0 >> 2) * 128;
;         bf16x8 b0 = *reinterpret_cast<const bf16x8*>(a);
;         bf16x8 b1 = *reinterpret_cast<const bf16x8*>(a + 32 * 256);
;         p0 = __builtin_amdgcn_mfma_f32_32x32x16_bf16(b0, qr[d0], p0, 0, 0, 0);
;         p1 = __builtin_amdgcn_mfma_f32_32x32x16_bf16(b1, qr[d0], p1, 0, 0, 0); }
; }
	ds_read_b128 v[114:117], v226 offset:256
	ds_read_b128 v[118:121], v226 offset:288
	ds_read_b128 v[98:101], v226 offset:384
	ds_read_b128 v[102:105], v226 offset:416
	ds_read_b128 v[122:125], v226 offset:320
	ds_read_b128 v[106:109], v226 offset:448
	ds_read_b128 v[126:129], v226 offset:352
	ds_read_b128 v[110:113], v226 offset:480
	ds_read_b128 v[180:183], v201 offset:32768
	ds_read_b128 v[184:187], v201 offset:40960
	v_exp_f32_e32 v97, v178
	v_add_f32_e32 v178, 0, v66
	v_add_f32_e32 v178, v67, v178
	s_waitcnt lgkmcnt(1)
	v_mfma_f32_32x32x16_bf16 v[114:129], v[180:183], v[154:157], v[114:129]
	v_add_f32_e32 v178, v68, v178
	v_add_f32_e32 v178, v69, v178
	v_add_f32_e32 v178, v70, v178
	v_add_f32_e32 v178, v71, v178
	v_add_f32_e32 v178, v72, v178
	v_add_f32_e32 v178, v73, v178
	v_add_f32_e32 v178, v74, v178
	s_waitcnt lgkmcnt(0)
	v_mfma_f32_32x32x16_bf16 v[98:113], v[184:187], v[154:157], v[98:113]
	ds_read_b128 v[180:183], v221 offset:32768
	ds_read_b128 v[184:187], v221 offset:40960
	v_add_f32_e32 v178, v75, v178
	v_add_f32_e32 v178, v76, v178
	v_add_f32_e32 v178, v77, v178
	v_exp_f32_e32 v82, v82
	v_add_f32_e32 v178, v78, v178
	v_exp_f32_e32 v83, v83
	s_waitcnt lgkmcnt(1)
	v_mfma_f32_32x32x16_bf16 v[114:129], v[180:183], v[130:133], v[114:129]
	v_add_f32_e32 v178, v79, v178
	v_exp_f32_e32 v84, v84
	v_add_f32_e32 v178, v80, v178
	v_exp_f32_e32 v85, v85
	v_add_f32_e32 v178, v81, v178
	v_exp_f32_e32 v86, v86
	v_add_f32_e32 v178, v82, v178
	s_waitcnt lgkmcnt(0)
	v_mfma_f32_32x32x16_bf16 v[98:113], v[184:187], v[130:133], v[98:113]
	ds_read_b128 v[180:183], v222 offset:32768
	ds_read_b128 v[184:187], v222 offset:40960
	v_exp_f32_e32 v87, v87
	v_add_f32_e32 v178, v83, v178
	v_exp_f32_e32 v88, v88
	v_add_f32_e32 v178, v84, v178
	v_exp_f32_e32 v89, v89
	v_add_f32_e32 v178, v85, v178
	s_waitcnt lgkmcnt(1)
	v_mfma_f32_32x32x16_bf16 v[114:129], v[180:183], v[158:161], v[114:129]
	v_exp_f32_e32 v90, v90
	v_add_f32_e32 v178, v86, v178
	v_exp_f32_e32 v91, v91
	v_add_f32_e32 v178, v87, v178
	v_exp_f32_e32 v92, v92
	v_add_f32_e32 v178, v88, v178
	v_exp_f32_e32 v93, v93
	s_waitcnt lgkmcnt(0)
	v_mfma_f32_32x32x16_bf16 v[98:113], v[184:187], v[158:161], v[98:113]
	ds_read_b128 v[180:183], v223 offset:32768
	ds_read_b128 v[184:187], v223 offset:40960
	v_add_f32_e32 v178, v89, v178
	v_exp_f32_e32 v94, v94
	v_add_f32_e32 v178, v90, v178
	v_exp_f32_e32 v95, v95
	v_add_f32_e32 v178, v91, v178
	v_exp_f32_e32 v96, v96
	s_waitcnt lgkmcnt(1)
	v_mfma_f32_32x32x16_bf16 v[114:129], v[180:183], v[138:141], v[114:129]
	v_add_f32_e32 v178, v92, v178
	v_add_f32_e32 v178, v93, v178
	v_add_f32_e32 v178, v94, v178
	v_add_f32_e32 v178, v95, v178
	v_add_f32_e32 v178, v96, v178
	v_add_f32_e32 v232, v97, v178
	v_mov_b32_e32 v233, v232
	s_waitcnt lgkmcnt(0)
	v_mfma_f32_32x32x16_bf16 v[98:113], v[184:187], v[138:141], v[98:113]
	ds_read_b128 v[180:183], v201 offset:32896
	ds_read_b128 v[184:187], v201 offset:41088
	v_permlane32_swap_b32_e32 v232, v233
	s_waitcnt lgkmcnt(1)
	v_mfma_f32_32x32x16_bf16 v[114:129], v[180:183], v[142:145], v[114:129]
	s_waitcnt lgkmcnt(0)
	v_mfma_f32_32x32x16_bf16 v[98:113], v[184:187], v[142:145], v[98:113]
	ds_read_b128 v[180:183], v221 offset:32896
	ds_read_b128 v[184:187], v221 offset:41088
	s_waitcnt lgkmcnt(1)
	v_mfma_f32_32x32x16_bf16 v[114:129], v[180:183], v[146:149], v[114:129]
	s_waitcnt lgkmcnt(0)
	v_mfma_f32_32x32x16_bf16 v[98:113], v[184:187], v[146:149], v[98:113]
	ds_read_b128 v[180:183], v222 offset:32896
	ds_read_b128 v[184:187], v222 offset:41088
	s_waitcnt lgkmcnt(1)
	v_mfma_f32_32x32x16_bf16 v[114:129], v[180:183], v[150:153], v[114:129]
	s_waitcnt lgkmcnt(0)
	v_mfma_f32_32x32x16_bf16 v[98:113], v[184:187], v[150:153], v[98:113]
	ds_read_b128 v[180:183], v223 offset:32896
	ds_read_b128 v[184:187], v223 offset:41088
	v_cvt_pk_bf16_f32 v178, v66, v67
	v_cvt_pk_bf16_f32 v179, v68, v69
	s_waitcnt lgkmcnt(1)
	v_mfma_f32_32x32x16_bf16 v[114:129], v[180:183], v[134:137], v[114:129]
	v_cvt_pk_bf16_f32 v180, v70, v71
	v_cvt_pk_bf16_f32 v181, v72, v73
	v_cvt_pk_bf16_f32 v182, v74, v75
	v_cvt_pk_bf16_f32 v183, v76, v77
	s_nop 0
	v_permlane32_swap_b32_e32 v178, v180
	s_waitcnt lgkmcnt(0)
	v_mfma_f32_32x32x16_bf16 v[98:113], v[184:187], v[134:137], v[98:113]
	v_cvt_pk_bf16_f32 v184, v78, v79
	v_cvt_pk_bf16_f32 v185, v80, v81
	v_cvt_pk_bf16_f32 v186, v82, v83
	v_cvt_pk_bf16_f32 v187, v84, v85
	v_cvt_pk_bf16_f32 v188, v86, v87
	v_cvt_pk_bf16_f32 v189, v88, v89
	v_cvt_pk_bf16_f32 v190, v90, v91
	v_cvt_pk_bf16_f32 v191, v92, v93
	v_cvt_pk_bf16_f32 v192, v94, v95
	v_cvt_pk_bf16_f32 v193, v96, v97
	v_permlane32_swap_b32_e32 v179, v181
	v_permlane32_swap_b32_e32 v182, v184
	v_permlane32_swap_b32_e32 v183, v185
	v_permlane32_swap_b32_e32 v186, v188
	v_permlane32_swap_b32_e32 v187, v189
	v_permlane32_swap_b32_e32 v190, v192
	v_permlane32_swap_b32_e32 v191, v193
	s_add_i32 s12, s77, 1
	s_cmp_lt_i32 s12, s76
	s_cselect_b64 s[74:75], -1, 0
	s_cmp_ge_i32 s12, s76
	s_cbranch_scc1 .LBB0_791
	s_add_i32 s12, s78, 0x41
	s_mul_hi_i32 s13, s12, 0x3000
	s_mulk_i32 s12, 0x3000
	s_add_u32 s12, s68, s12
	s_addc_u32 s13, s69, s13
	v_lshl_add_u64 v[166:167], v[196:197], 1, s[12:13]
	v_lshl_add_u64 v[174:175], v[204:205], 1, s[12:13]
	global_load_dwordx4 v[162:165], v[166:167], off offset:2048
	s_nop 0
	global_load_dwordx4 v[166:169], v[166:167], off
	s_nop 0
	global_load_dwordx4 v[170:173], v[174:175], off offset:2048
	s_nop 0
	global_load_dwordx4 v[174:177], v[174:175], off

; #define SBAR() __builtin_amdgcn_sched_barrier(0)
; #define SLOAD_H(Kp, k0) do { const bf16_t* kb__ = (Kp) + (size_t)(k0) * PW;     \
;                          S.st_v0 = load8(kb__ + voff0 + VOFF); S.st_v1 = load8(kb__ + voff1 + VOFF);              \
;                          S.st_k0 = load8(kb__ + voff0); S.st_k1 = load8(kb__ + voff1); } while (0)
; __device__ __forceinline__ void finishSM(f32x16& p0, f32x16& p1, float alpha, float& l_reg, bf16x8& pa0, bf16x8& pa1, bf16x8& pa2, bf16x8& pa3) {
; #pragma unroll
;     for (int r = 0; r < 16; ++r) p1[r] = __builtin_amdgcn_exp2f(p1[r]);
;     float ps = 0;
; #pragma unroll
;     for (int r = 0; r < 16; ++r) ps += p0[r];
; #pragma unroll
;     for (int r = 0; r < 16; ++r) ps += p1[r];
;     { auto rr = __builtin_amdgcn_permlane32_swap(__float_as_uint(ps), __float_as_uint(ps), false, false);
;       ps = __uint_as_float(rr[0]) + __uint_as_float(rr[1]); }
;     l_reg = l_reg * alpha + ps;
;     ...
;     PK4(p0, 0, pa0); PK4(p0, 8, pa1); PK4(p1, 0, pa2); PK4(p1, 8, pa3);
;     ...
; }
; template <int VB>
; __device__ __forceinline__ void pv_tile(f32x16* o, int vb0, bf16x8 pa0, bf16x8 pa1, bf16x8 pa2, bf16x8 pa3) {
;     ...
;     PV_D0(0); PV_D0(1); PV_D0(2); PV_D0(3);
;     ...
; }
; __device__ __forceinline__ bool fox_block(const BlockRef& cur, BlockRef& nxt, unsigned* ctr, const unsigned* nrm, bf16_t* PROJ, bf16_t* MIX, char* lds, Seam& S, const float* __restrict__ CF, const float* __restrict__ fnorm) {
;     ...
;     SLOAD_H(nxt.K, nxt.jlo * KVBLK); SBAR();
;     { const bf16_t* qb__ = nxt.Q + (size_t)(wid * QBLK) * PW;
; #pragma unroll
;     for (int d0 = 0; d0 < 8; ++d0) S.qr[d0] = load8(qb__ + voffq + d0 * 16); }
;     SBAR();
;     finishSM(pA0, pA1, alA, l_reg, pa0, pa1, pa2, pa3); SBAR();
;     pv_tile<0>(o, vb0, pa0, pa1, pa2, pa3);
.LBB0_814:
	s_mul_i32 s10, s84, 0x3000
	s_mul_hi_i32 s11, s84, 0x3000
	s_add_u32 s10, s78, s10
	s_addc_u32 s11, s79, s11
	v_mov_b32_e32 v205, v197
	v_lshl_add_u64 v[102:103], v[196:197], 1, s[10:11]
	v_lshl_add_u64 v[110:111], v[204:205], 1, s[10:11]
	global_load_dwordx4 v[98:101], v[102:103], off offset:2048
	s_nop 0
	global_load_dwordx4 v[102:105], v[102:103], off
	s_nop 0
	global_load_dwordx4 v[106:109], v[110:111], off offset:2048
	s_nop 0
	global_load_dwordx4 v[110:113], v[110:111], off
	v_mul_u32_u24_e32 v130, 0x1800, v211
	s_mul_i32 s10, s72, 0x3000
	s_mul_hi_i32 s11, s72, 0x3000
	s_add_u32 s10, s82, s10
	v_lshlrev_b32_e32 v130, 1, v130
	s_addc_u32 s11, s83, s11
	v_lshl_or_b32 v196, v203, 4, v130
	v_lshl_add_u64 v[134:135], s[10:11], 0, v[196:197]
	global_load_dwordx4 v[154:157], v[134:135], off
	global_load_dwordx4 v[130:133], v[134:135], off offset:32
	global_load_dwordx4 v[158:161], v[134:135], off offset:64
	global_load_dwordx4 v[138:141], v[134:135], off offset:96
	global_load_dwordx4 v[142:145], v[134:135], off offset:128
	global_load_dwordx4 v[146:149], v[134:135], off offset:160
	global_load_dwordx4 v[150:153], v[134:135], off offset:192
	s_nop 0
	global_load_dwordx4 v[134:137], v[134:135], off offset:224
	v_exp_f32_e32 v189, v114
	v_add_f32_e32 v114, 0, v175
	v_add_f32_e32 v114, v177, v114
	v_add_f32_e32 v114, v173, v114
	v_add_f32_e32 v114, v176, v114
	v_add_f32_e32 v114, v172, v114
	v_add_f32_e32 v114, v174, v114
	v_add_f32_e32 v114, v170, v114
	v_add_f32_e32 v114, v171, v114
	v_add_f32_e32 v114, v166, v114
	v_add_f32_e32 v114, v169, v114
	v_add_f32_e32 v114, v164, v114
	v_add_f32_e32 v114, v167, v114
	v_exp_f32_e32 v128, v128
	v_add_f32_e32 v114, v162, v114
	v_exp_f32_e32 v129, v129
	v_add_f32_e32 v114, v168, v114
	v_exp_f32_e32 v126, v126
	v_add_f32_e32 v114, v163, v114
	v_exp_f32_e32 v127, v127
	v_add_f32_e32 v114, v165, v114
	v_exp_f32_e32 v179, v124
	v_add_f32_e32 v114, v128, v114
	v_exp_f32_e32 v180, v125
	v_add_f32_e32 v114, v129, v114
	v_exp_f32_e32 v181, v122
	v_add_f32_e32 v114, v126, v114
	v_exp_f32_e32 v182, v123
	v_add_f32_e32 v114, v127, v114
	v_exp_f32_e32 v183, v120
	v_add_f32_e32 v114, v179, v114
	v_exp_f32_e32 v184, v121
	v_add_f32_e32 v114, v180, v114
	v_exp_f32_e32 v185, v118
	v_add_f32_e32 v114, v181, v114
	v_exp_f32_e32 v186, v119
	v_add_f32_e32 v114, v182, v114
	v_exp_f32_e32 v187, v116
	v_add_f32_e32 v114, v183, v114
	v_exp_f32_e32 v188, v117
	v_add_f32_e32 v114, v184, v114
	v_add_f32_e32 v114, v185, v114
	v_exp_f32_e32 v115, v115
	v_add_f32_e32 v114, v186, v114
	v_add_f32_e32 v114, v187, v114
	v_add_f32_e32 v114, v188, v114
	v_add_f32_e32 v114, v189, v114
	v_add_f32_e32 v114, v115, v114
	v_mov_b32_e32 v116, v114
	s_nop 1
	v_permlane32_swap_b32_e32 v114, v116
	v_add_f32_e32 v114, v114, v116
	v_fmac_f32_e32 v114, v219, v218
	v_cvt_pk_bf16_f32 v116, v175, v177
	v_cvt_pk_bf16_f32 v117, v173, v176
	v_cvt_pk_bf16_f32 v118, v172, v174
	v_cvt_pk_bf16_f32 v119, v170, v171
	v_cvt_pk_bf16_f32 v120, v166, v169
	v_cvt_pk_bf16_f32 v121, v164, v167
	v_cvt_pk_bf16_f32 v122, v162, v168
	v_cvt_pk_bf16_f32 v123, v163, v165
	v_cvt_pk_bf16_f32 v124, v128, v129
	v_cvt_pk_bf16_f32 v125, v126, v127
	v_cvt_pk_bf16_f32 v126, v179, v180
	v_cvt_pk_bf16_f32 v127, v181, v182
	v_cvt_pk_bf16_f32 v162, v183, v184
	v_cvt_pk_bf16_f32 v163, v185, v186
	v_cvt_pk_bf16_f32 v164, v187, v188
	v_cvt_pk_bf16_f32 v165, v189, v115
	s_nop 0
	v_permlane32_swap_b32_e32 v116, v118
	v_permlane32_swap_b32_e32 v117, v119
	v_permlane32_swap_b32_e32 v120, v122
	v_permlane32_swap_b32_e32 v121, v123
	v_permlane32_swap_b32_e32 v124, v126
	v_permlane32_swap_b32_e32 v125, v127
	v_permlane32_swap_b32_e32 v162, v164
	v_permlane32_swap_b32_e32 v163, v165
	ds_read_b64_tr_b16 v[166:167], v216 offset:0
	ds_read_b64_tr_b16 v[168:169], v216 offset:0x800
	ds_read_b64_tr_b16 v[170:171], v216 offset:0x1000
	ds_read_b64_tr_b16 v[172:173], v216 offset:0x1800
	ds_read_b64_tr_b16 v[174:175], v216 offset:0x2000
	ds_read_b64_tr_b16 v[176:177], v216 offset:0x2800
	ds_read_b64_tr_b16 v[180:181], v216 offset:0x3000
	ds_read_b64_tr_b16 v[182:183], v216 offset:0x3800
	s_waitcnt lgkmcnt(0)
	s_nop 0
	v_mfma_f32_32x32x16_bf16 v[50:65], v[116:119], v[166:169], v[50:65]
	ds_read_b64_tr_b16 v[166:167], v216 offset:0x200
	ds_read_b64_tr_b16 v[168:169], v216 offset:0xa00
	v_mfma_f32_32x32x16_bf16 v[50:65], v[120:123], v[170:173], v[50:65]
	ds_read_b64_tr_b16 v[170:171], v216 offset:0x1200
	ds_read_b64_tr_b16 v[172:173], v216 offset:0x1a00
	v_mfma_f32_32x32x16_bf16 v[50:65], v[124:127], v[174:177], v[50:65]
	ds_read_b64_tr_b16 v[174:175], v216 offset:0x2200
	ds_read_b64_tr_b16 v[176:177], v216 offset:0x2a00
	ds_read_b64_tr_b16 v[184:185], v216 offset:0x3200
	ds_read_b64_tr_b16 v[186:187], v216 offset:0x3a00
	s_waitcnt lgkmcnt(0)
	v_mfma_f32_32x32x16_bf16 v[50:65], v[162:165], v[180:183], v[50:65]
	v_mfma_f32_32x32x16_bf16 v[34:49], v[116:119], v[166:169], v[34:49]
	ds_read_b64_tr_b16 v[166:167], v216 offset:0x400
	ds_read_b64_tr_b16 v[168:169], v216 offset:0xc00
	v_mfma_f32_32x32x16_bf16 v[34:49], v[120:123], v[170:173], v[34:49]
	ds_read_b64_tr_b16 v[170:171], v216 offset:0x1400
	ds_read_b64_tr_b16 v[172:173], v216 offset:0x1c00
	v_mfma_f32_32x32x16_bf16 v[34:49], v[124:127], v[174:177], v[34:49]
	ds_read_b64_tr_b16 v[174:175], v216 offset:0x2400
	ds_read_b64_tr_b16 v[176:177], v216 offset:0x2c00
	ds_read_b64_tr_b16 v[180:181], v216 offset:0x3400
	ds_read_b64_tr_b16 v[182:183], v216 offset:0x3c00
	s_waitcnt lgkmcnt(0)
	v_mfma_f32_32x32x16_bf16 v[34:49], v[162:165], v[184:187], v[34:49]
	v_mfma_f32_32x32x16_bf16 v[18:33], v[116:119], v[166:169], v[18:33]
	ds_read_b64_tr_b16 v[166:167], v216 offset:0x600
	ds_read_b64_tr_b16 v[168:169], v216 offset:0xe00
	v_mfma_f32_32x32x16_bf16 v[18:33], v[120:123], v[170:173], v[18:33]
	ds_read_b64_tr_b16 v[170:171], v216 offset:0x1600
	ds_read_b64_tr_b16 v[172:173], v216 offset:0x1e00
	v_mfma_f32_32x32x16_bf16 v[18:33], v[124:127], v[174:177], v[18:33]
	ds_read_b64_tr_b16 v[174:175], v216 offset:0x2600
	ds_read_b64_tr_b16 v[176:177], v216 offset:0x2e00
	ds_read_b64_tr_b16 v[184:185], v216 offset:0x3600
	ds_read_b64_tr_b16 v[186:187], v216 offset:0x3e00
	s_waitcnt lgkmcnt(0)
	v_mfma_f32_32x32x16_bf16 v[18:33], v[162:165], v[180:183], v[18:33]
	v_mfma_f32_32x32x16_bf16 v[2:17], v[116:119], v[166:169], v[2:17]
	s_andn2_b64 vcc, exec, s[12:13]
	v_mfma_f32_32x32x16_bf16 v[2:17], v[120:123], v[170:173], v[2:17]
	v_mfma_f32_32x32x16_bf16 v[2:17], v[124:127], v[174:177], v[2:17]
	v_mfma_f32_32x32x16_bf16 v[2:17], v[162:165], v[184:187], v[2:17]
	s_cbranch_vccnz .LBB0_822
; #define RESC(a) do { if (__any((a) < 1.f)) { if (hi == 0) al_l[r32] = (a); asm volatile("s_waitcnt lgkmcnt(0)" ::: "memory");              \
;                      _Pragma("unroll") for (int d_ = 0; d_ < 4; ++d_) _Pragma("unroll") for (int r = 0; r < 16; ++r) o[d_][r] *= al_l[crow(r, hi)]; } } while (0)
; #define MASKT(P0_, P1_, t) do { const int kb_ = KBASE(t); if (kb_ + KVBLK - 1 > qlo) mask_tile(P0_, P1_, qm - kb_, WBIG); } while (0)
; __device__ __forceinline__ void mask_tile(f32x16& p0, f32x16& p1, int dq, unsigned W) {
;     const float NEG = -__builtin_inff();
; #pragma unroll
;     for (int r = 0; r < 16; ++r) {
;         const int c = (r & 3) + 8 * (r >> 2);
;         if ((unsigned)(dq - c) >= W) p0[r] = NEG;
;         if ((unsigned)(dq - c - 32) >= W) p1[r] = NEG;
;     }
; }
; __device__ __forceinline__ bool fox_block(const BlockRef& cur, BlockRef& nxt, unsigned* ctr, const unsigned* nrm, bf16_t* PROJ, bf16_t* MIX, char* lds, Seam& S, const float* __restrict__ CF, const float* __restrict__ fnorm) {
;     ...
;     if (even) { MASKT(pB0, pB1, NT - 1); partialSM(pB0, pB1, m_reg, mnB, alB); __syncthreads(); RESC(alB);
	s_lshl_b32 s10, s31, 6
	s_or_b32 s11, s10, 63
	s_cmp_le_i32 s11, s73
	s_cbranch_scc1 .LBB0_817
	v_subrev_u32_e32 v115, s10, v217
	v_cmp_gt_u32_e32 vcc, 2.0, v115
	v_add_u32_e32 v116, 0xbfffffe0, v115
	s_nop 0
	v_cndmask_b32_e32 v66, v208, v66, vcc
	v_cmp_lt_u32_e32 vcc, s95, v116
	v_add_u32_e32 v116, 0xbfffffff, v115
	s_nop 0
	v_cndmask_b32_e32 v82, v208, v82, vcc
	v_cmp_lt_u32_e32 vcc, s95, v116
	v_add_u32_e32 v116, 0xbfffffdf, v115
	s_nop 0
	v_cndmask_b32_e32 v67, v208, v67, vcc
	v_cmp_lt_u32_e32 vcc, s95, v116
	v_add_u32_e32 v116, 0xbffffffe, v115
	s_nop 0
	v_cndmask_b32_e32 v83, v208, v83, vcc
	v_cmp_lt_u32_e32 vcc, s95, v116
	v_add_u32_e32 v116, 0xbfffffde, v115
	s_nop 0
	v_cndmask_b32_e32 v68, v208, v68, vcc
	v_cmp_lt_u32_e32 vcc, s95, v116
	v_add_u32_e32 v116, 0xbffffffd, v115
	s_nop 0
	v_cndmask_b32_e32 v84, v208, v84, vcc
	v_cmp_lt_u32_e32 vcc, s95, v116
	v_add_u32_e32 v116, 0xbfffffdd, v115
	s_nop 0
	v_cndmask_b32_e32 v69, v208, v69, vcc
	v_cmp_lt_u32_e32 vcc, s95, v116
	v_add_u32_e32 v116, 0xbffffff8, v115
	s_nop 0
	v_cndmask_b32_e32 v85, v208, v85, vcc
	v_cmp_lt_u32_e32 vcc, s95, v116
	v_add_u32_e32 v116, 0xbfffffd8, v115
	s_nop 0
	v_cndmask_b32_e32 v70, v208, v70, vcc
	v_cmp_lt_u32_e32 vcc, s95, v116
	v_add_u32_e32 v116, 0xbffffff7, v115
	s_nop 0
	v_cndmask_b32_e32 v86, v208, v86, vcc
	v_cmp_lt_u32_e32 vcc, s95, v116
	v_add_u32_e32 v116, 0xbfffffd7, v115
	s_nop 0
	v_cndmask_b32_e32 v71, v208, v71, vcc
	v_cmp_lt_u32_e32 vcc, s95, v116
	v_add_u32_e32 v116, 0xbffffff6, v115
	s_nop 0
	v_cndmask_b32_e32 v87, v208, v87, vcc
	v_cmp_lt_u32_e32 vcc, s95, v116
	v_add_u32_e32 v116, 0xbfffffd6, v115
	s_nop 0
	v_cndmask_b32_e32 v72, v208, v72, vcc
	v_cmp_lt_u32_e32 vcc, s95, v116
	v_add_u32_e32 v116, 0xbffffff5, v115
	s_nop 0
	v_cndmask_b32_e32 v88, v208, v88, vcc
	v_cmp_lt_u32_e32 vcc, s95, v116
	v_add_u32_e32 v116, 0xbfffffd5, v115
	s_nop 0
	v_cndmask_b32_e32 v73, v208, v73, vcc
	v_cmp_lt_u32_e32 vcc, s95, v116
	v_add_u32_e32 v116, 0xbffffff0, v115
	s_nop 0
	v_cndmask_b32_e32 v89, v208, v89, vcc
	v_cmp_lt_u32_e32 vcc, s95, v116
	v_add_u32_e32 v116, 0xbfffffd0, v115
	s_nop 0
	v_cndmask_b32_e32 v74, v208, v74, vcc
	v_cmp_lt_u32_e32 vcc, s95, v116
	v_add_u32_e32 v116, 0xbfffffef, v115
	s_nop 0
	v_cndmask_b32_e32 v90, v208, v90, vcc
	v_cmp_lt_u32_e32 vcc, s95, v116
	v_add_u32_e32 v116, 0xbfffffcf, v115
	s_nop 0
	v_cndmask_b32_e32 v75, v208, v75, vcc
	v_cmp_lt_u32_e32 vcc, s95, v116
	v_add_u32_e32 v116, 0xbfffffee, v115
	s_nop 0
	v_cndmask_b32_e32 v91, v208, v91, vcc
	v_cmp_lt_u32_e32 vcc, s95, v116
	v_add_u32_e32 v116, 0xbfffffce, v115
	s_nop 0
	v_cndmask_b32_e32 v76, v208, v76, vcc
	v_cmp_lt_u32_e32 vcc, s95, v116
	v_add_u32_e32 v116, 0xbfffffed, v115
	s_nop 0
	v_cndmask_b32_e32 v92, v208, v92, vcc
	v_cmp_lt_u32_e32 vcc, s95, v116
	v_add_u32_e32 v116, 0xbfffffcd, v115
	s_nop 0
	v_cndmask_b32_e32 v77, v208, v77, vcc
	v_cmp_lt_u32_e32 vcc, s95, v116
	v_add_u32_e32 v116, 0xbfffffe8, v115
	s_nop 0
	v_cndmask_b32_e32 v93, v208, v93, vcc
	v_cmp_lt_u32_e32 vcc, s95, v116
	v_add_u32_e32 v116, 0xbfffffc8, v115
	s_nop 0
	v_cndmask_b32_e32 v78, v208, v78, vcc
	v_cmp_lt_u32_e32 vcc, s95, v116
	v_add_u32_e32 v116, 0xbfffffe7, v115
	s_nop 0
	v_cndmask_b32_e32 v94, v208, v94, vcc
	v_cmp_lt_u32_e32 vcc, s95, v116
	v_add_u32_e32 v116, 0xbfffffc7, v115
	s_nop 0
	v_cndmask_b32_e32 v79, v208, v79, vcc
	v_cmp_lt_u32_e32 vcc, s95, v116
	v_add_u32_e32 v116, 0xbfffffe6, v115
	s_nop 0
	v_cndmask_b32_e32 v95, v208, v95, vcc
	v_cmp_lt_u32_e32 vcc, s95, v116
	v_add_u32_e32 v116, 0xbfffffc6, v115
	s_nop 0
	v_cndmask_b32_e32 v80, v208, v80, vcc
	v_cmp_lt_u32_e32 vcc, s95, v116
	v_add_u32_e32 v116, 0xbfffffe5, v115
	v_add_u32_e32 v115, 0xbfffffc5, v115
	v_cndmask_b32_e32 v96, v208, v96, vcc
	v_cmp_lt_u32_e32 vcc, s95, v116
	s_nop 1
	v_cndmask_b32_e32 v81, v208, v81, vcc
	v_cmp_lt_u32_e32 vcc, s95, v115
	s_nop 1
	v_cndmask_b32_e32 v97, v208, v97, vcc

; #define VMW() asm volatile("s_waitcnt vmcnt(0)" ::: "memory")
; #define SLOAD_H(Kp, k0) do { const bf16_t* kb__ = (Kp) + (size_t)(k0) * PW;     \
;                          S.st_v0 = load8(kb__ + voff0 + VOFF); S.st_v1 = load8(kb__ + voff1 + VOFF);              \
;                          S.st_k0 = load8(kb__ + voff0); S.st_k1 = load8(kb__ + voff1); } while (0)
; #define SWRITE_HK(bf) do { *(bf16x8*)(K_lds + (bf) * SHM_K + kws) = S.st_k0; *(bf16x8*)(K_lds + (bf) * SHM_K + kws + 32 * 256) = S.st_k1; } while (0)
; __device__ __forceinline__ void fox_prime(const BlockRef& cur, char* lds, Seam& S) {
;     int tidl_ = threadIdx.x; asm volatile("" : "+v"(tidl_));
;     const int tid = tidl_, wid = __builtin_amdgcn_readfirstlane(tid >> 6), lane = tid & 63, r32 = lane & 31, hi = lane >> 5;
;     const int sr = tid >> 4, sc = (tid & 15) * 8, kws = KSWZ(sr, sc * 2); char* K_lds = lds + 2 * SHM_V;
;     const unsigned voff0 = (unsigned)(sr * PW + sc), voff1 = voff0 + 32u * PW, voffq = (unsigned)(r32 * PW + hi * 8);
;     { const bf16_t* qb__ = cur.Q + (size_t)(wid * QBLK) * PW;
; #pragma unroll
;     for (int d0 = 0; d0 < 8; ++d0) S.qr[d0] = load8(qb__ + voffq + d0 * 16); }
;     SLOAD_H(cur.K, cur.jlo * KVBLK); VMW(); SWRITE_HK(0);
;     __syncthreads();
; }
.LBB0_2191:
	s_mul_i32 s3, s30, 0x3000
	s_add_u32 s3, s43, s3
	s_addc_u32 s8, s40, 0
	s_lshl_b32 s9, s22, 8
	s_add_u32 s3, s3, s9
	s_addc_u32 s8, s8, 0
	s_add_u32 s66, s3, 0x1800
	s_addc_u32 s67, s8, 0
	s_add_u32 s68, s39, s9
	s_addc_u32 s69, s34, 0
	s_lshl_b32 s3, s30, 12
	s_add_u32 s3, s41, s3
	s_addc_u32 s8, s36, 0
	s_add_u32 s3, s3, s9
	s_addc_u32 s8, s8, 0
	s_add_u32 s70, s3, 0x800
	v_readfirstlane_b32 s3, v3
	v_mov_b32_e32 v3, v194
	s_addc_u32 s71, s8, 0
	s_nop 0
	v_readfirstlane_b32 s8, v3
	s_ashr_i32 s8, s8, 1
	v_and_b32_e32 v4, 31, v3
	s_andn2_b32 s8, s8, 31
	v_mul_u32_u24_e32 v4, 0x1800, v4
	v_lshrrev_b32_e32 v5, 2, v3
	s_mul_hi_i32 s9, s8, 0x3000
	s_mulk_i32 s8, 0x3000
	v_and_or_b32 v4, v5, 8, v4
	s_add_u32 s8, s66, s8
	s_addc_u32 s9, s67, s9
	v_lshlrev_b32_e32 v196, 1, v4
	v_lshl_add_u64 v[4:5], s[8:9], 0, v[196:197]
	global_load_dwordx4 v[154:157], v[4:5], off
	global_load_dwordx4 v[130:133], v[4:5], off offset:32
	v_ashrrev_i32_e32 v10, 4, v3
	v_lshlrev_b32_e32 v7, 3, v3
	s_lshl_b32 s8, s3, 6
	s_mul_i32 s9, s3, 0xc0000
	v_mul_lo_u32 v6, v10, s92
	v_and_b32_e32 v11, 0x78, v7
	s_mul_hi_i32 s10, s8, 0x3000
	s_add_u32 s8, s68, s9
	v_or_b32_e32 v196, v6, v11
	s_addc_u32 s9, s69, s10
	v_add_u32_e32 v6, 0x30000, v196
	v_lshl_add_u64 v[8:9], v[196:197], 1, s[8:9]
	v_mov_b32_e32 v7, v197
	v_lshl_add_u64 v[6:7], v[6:7], 1, s[8:9]
	global_load_dwordx4 v[98:101], v[8:9], off offset:2048
	global_load_dwordx4 v[102:105], v[8:9], off
	global_load_dwordx4 v[106:109], v[6:7], off offset:2048
	global_load_dwordx4 v[110:113], v[6:7], off
	global_load_dwordx4 v[158:161], v[4:5], off offset:64
	global_load_dwordx4 v[138:141], v[4:5], off offset:96
	global_load_dwordx4 v[142:145], v[4:5], off offset:128
	global_load_dwordx4 v[146:149], v[4:5], off offset:160
	global_load_dwordx4 v[150:153], v[4:5], off offset:192
	global_load_dwordx4 v[134:137], v[4:5], off offset:224
	s_movk_i32 s8, 0x70
	v_lshlrev_b32_e32 v5, 1, v11
	s_waitcnt vmcnt(0)
	v_lshlrev_b32_e32 v4, 8, v10
	v_bitop3_b32 v3, v5, v3, s8 bitop3:0x78
	v_add3_u32 v3, s87, v4, v3
	v_cmp_lt_u32_e64 s[8:9], 63, v2
	s_waitcnt vmcnt(0) lgkmcnt(0)
	ds_write_b128 v3, v[102:105] offset:32768
	ds_write_b128 v3, v[110:113] offset:40960
	s_waitcnt lgkmcnt(0)
	s_barrier
	s_branch .LBB0_2193
